# stack1 + attention: C-init broadcast via v_mov_b64, 12 conservative s_nop 0 between plain VALU adds removed (bit-identical)
# speedup vs baseline: 1.0055x; 1.0008x over previous
.LBB0_675:
	s_add_i32 s85, s86, s89
	s_and_b32 s84, s77, 1
	s_addk_i32 s85, 0xc000
	s_add_u32 vcc_lo, s96, s85
	s_addc_u32 vcc_hi, s78, 0
	v_lshl_add_u64 v[66:67], vcc, 0, v[178:179]
	v_add_co_u32_e32 v68, vcc, s92, v66
	s_mul_i32 s85, s84, 0x4400
	s_nop 0
	v_addc_co_u32_e32 v69, vcc, 0, v67, vcc
	global_load_dwordx4 v[146:149], v[66:67], off
	global_load_dwordx4 v[150:153], v[68:69], off
	v_lshrrev_b32_e32 v66, s1, v169
	v_and_b32_e32 v66, 1, v66
	v_cmp_eq_u32_e32 vcc, 1, v66
	s_nop 1
	v_cndmask_b32_e64 v66, v188, -v170, vcc
	v_mov_b32_e32 v67, v66
	v_mov_b64_e32 v[68:69], v[66:67]
	v_mov_b64_e32 v[70:71], v[66:67]
	v_mov_b64_e32 v[72:73], v[66:67]
	v_mov_b64_e32 v[74:75], v[66:67]
	v_mov_b64_e32 v[76:77], v[66:67]
	v_mov_b64_e32 v[78:79], v[66:67]
	v_mov_b64_e32 v[80:81], v[66:67]
	s_waitcnt lgkmcnt(3)
	s_nop 0
	v_mfma_f32_32x32x16_bf16 v[82:97], v[172:175], v[114:117], v[66:81]
	ds_read_b128 v[172:175], v171 offset:64
	ds_read_b128 v[204:207], v171 offset:96
	ds_read_b128 v[208:211], v171 offset:8768
	ds_read_b128 v[212:215], v171 offset:8800
	s_waitcnt lgkmcnt(6)
	v_mfma_f32_32x32x16_bf16 v[82:97], v[184:187], v[118:121], v[82:97]
	s_waitcnt lgkmcnt(3)
	v_mfma_f32_32x32x16_bf16 v[82:97], v[172:175], v[122:125], v[82:97]
	ds_read_b128 v[172:175], v171 offset:128
	ds_read_b128 v[184:187], v171 offset:160
	ds_read_b128 v[216:219], v171 offset:8832
	ds_read_b128 v[220:223], v171 offset:8864
	s_waitcnt lgkmcnt(6)
	v_mfma_f32_32x32x16_bf16 v[82:97], v[204:207], v[126:129], v[82:97]
	s_waitcnt lgkmcnt(3)
	v_mfma_f32_32x32x16_bf16 v[82:97], v[172:175], v[130:133], v[82:97]
	ds_read_b128 v[172:175], v171 offset:192
	ds_read_b128 v[204:207], v171 offset:224
	ds_read_b128 v[224:227], v171 offset:8896
	ds_read_b128 v[228:231], v171 offset:8928
	s_waitcnt lgkmcnt(6)
	v_mfma_f32_32x32x16_bf16 v[82:97], v[184:187], v[134:137], v[82:97]
	s_waitcnt lgkmcnt(3)
	v_mfma_f32_32x32x16_bf16 v[82:97], v[172:175], v[138:141], v[82:97]
	s_waitcnt lgkmcnt(2)
	v_mfma_f32_32x32x16_bf16 v[82:97], v[204:207], v[142:145], v[82:97]
	v_mfma_f32_32x32x16_bf16 v[66:81], v[196:199], v[114:117], v[66:81]
	s_xor_b32 s85, s84, 1
	s_mul_i32 vcc_lo, s85, 0x5000
	v_add_u32_e32 v171, vcc_lo, v195
	ds_read_b64_tr_b16 v[174:175], v171 offset:37376
	s_nop 6
	v_exp_f32_e32 v82, v82
	v_exp_f32_e32 v83, v83
	v_exp_f32_e32 v84, v84
	v_mfma_f32_32x32x16_bf16 v[66:81], v[200:203], v[118:121], v[66:81]
	ds_read_b64_tr_b16 v[172:173], v171 offset:34816
	ds_read_b64_tr_b16 v[184:185], v171 offset:34880
	ds_read_b64_tr_b16 v[196:197], v171 offset:34944
	ds_read_b64_tr_b16 v[200:201], v171 offset:35008
	ds_read_b64_tr_b16 v[186:187], v171 offset:37440
	ds_read_b64_tr_b16 v[198:199], v171 offset:37504
	ds_read_b64_tr_b16 v[202:203], v171 offset:37568
	v_exp_f32_e32 v85, v85
	v_mfma_f32_32x32x16_bf16 v[66:81], v[208:211], v[122:125], v[66:81]
	v_mfma_f32_32x32x16_bf16 v[66:81], v[212:215], v[126:129], v[66:81]
	v_mfma_f32_32x32x16_bf16 v[66:81], v[216:219], v[130:133], v[66:81]
	v_mfma_f32_32x32x16_bf16 v[66:81], v[220:223], v[134:137], v[66:81]
	s_waitcnt lgkmcnt(9)
	v_mfma_f32_32x32x16_bf16 v[66:81], v[224:227], v[138:141], v[66:81]
	s_waitcnt lgkmcnt(8)
	v_mfma_f32_32x32x16_bf16 v[66:81], v[228:231], v[142:145], v[66:81]
	s_waitcnt lgkmcnt(6)
	v_mfma_f32_32x32x16_bf16 v[50:65], v[172:175], v[158:161], v[50:65]
	s_nop 9
	v_exp_f32_e32 v66, v66
	v_exp_f32_e32 v67, v67
	v_exp_f32_e32 v68, v68
	v_exp_f32_e32 v69, v69
	v_add_f32_e32 v172, v179, v82
	v_add_f32_e32 v173, v179, v66
	s_waitcnt lgkmcnt(2)
	v_mfma_f32_32x32x16_bf16 v[34:49], v[184:187], v[158:161], v[34:49]
	v_add_f32_e32 v172, v172, v83
	v_add_f32_e32 v173, v173, v67
	v_add_f32_e32 v172, v172, v84
	v_add_f32_e32 v173, v173, v68
	v_add_f32_e32 v176, v172, v85
	s_waitcnt lgkmcnt(1)
	v_mfma_f32_32x32x16_bf16 v[18:33], v[196:199], v[158:161], v[18:33]
	v_add_f32_e32 v177, v173, v69
	s_waitcnt lgkmcnt(0)
	v_mfma_f32_32x32x16_bf16 v[2:17], v[200:203], v[158:161], v[2:17]
	ds_read_b64_tr_b16 v[160:161], v171 offset:42496
	ds_read_b64_tr_b16 v[158:159], v171 offset:39936
	ds_read_b64_tr_b16 v[172:173], v171 offset:40000
	v_exp_f32_e32 v86, v86
	v_exp_f32_e32 v70, v70
	v_exp_f32_e32 v87, v87
	s_waitcnt lgkmcnt(1)
	v_mfma_f32_32x32x16_bf16 v[50:65], v[158:161], v[154:157], v[50:65]
	ds_read_b64_tr_b16 v[174:175], v171 offset:42560
	ds_read_b64_tr_b16 v[158:159], v171 offset:40064
	ds_read_b64_tr_b16 v[184:185], v171 offset:40128
	ds_read_b64_tr_b16 v[160:161], v171 offset:42624
	ds_read_b64_tr_b16 v[186:187], v171 offset:42688
	v_exp_f32_e32 v71, v71
	v_exp_f32_e32 v88, v88
	v_exp_f32_e32 v72, v72
	v_exp_f32_e32 v89, v89
	v_exp_f32_e32 v73, v73
	s_waitcnt lgkmcnt(4)
	v_mfma_f32_32x32x16_bf16 v[34:49], v[172:175], v[154:157], v[34:49]
	v_add_f32_e32 v172, v176, v86
	v_add_f32_e32 v173, v177, v70
	v_add_f32_e32 v172, v172, v87
	v_add_f32_e32 v173, v173, v71
	s_waitcnt lgkmcnt(1)
	v_mfma_f32_32x32x16_bf16 v[18:33], v[158:161], v[154:157], v[18:33]
	v_add_f32_e32 v158, v172, v88
	v_add_f32_e32 v159, v173, v72
	v_add_f32_e32 v176, v158, v89
	v_add_f32_e32 v177, v159, v73
	s_waitcnt lgkmcnt(0)
	v_mfma_f32_32x32x16_bf16 v[2:17], v[184:187], v[154:157], v[2:17]
	ds_read_b64_tr_b16 v[156:157], v171 offset:47616
	ds_read_b64_tr_b16 v[154:155], v171 offset:45056
	ds_read_b64_tr_b16 v[158:159], v171 offset:45120
	v_exp_f32_e32 v90, v90
	v_exp_f32_e32 v74, v74
	v_exp_f32_e32 v91, v91
	s_waitcnt lgkmcnt(1)
	v_mfma_f32_32x32x16_bf16 v[50:65], v[154:157], v[110:113], v[50:65]
	ds_read_b64_tr_b16 v[160:161], v171 offset:47680
	ds_read_b64_tr_b16 v[154:155], v171 offset:45184
	ds_read_b64_tr_b16 v[172:173], v171 offset:45248
	ds_read_b64_tr_b16 v[156:157], v171 offset:47744
	ds_read_b64_tr_b16 v[174:175], v171 offset:47808
	v_exp_f32_e32 v75, v75
	v_exp_f32_e32 v92, v92
	v_exp_f32_e32 v76, v76
	v_exp_f32_e32 v93, v93
	v_exp_f32_e32 v77, v77
	s_waitcnt lgkmcnt(4)
	v_mfma_f32_32x32x16_bf16 v[34:49], v[158:161], v[110:113], v[34:49]
	v_add_f32_e32 v158, v176, v90
	v_add_f32_e32 v159, v177, v74
	v_add_f32_e32 v158, v158, v91
	v_add_f32_e32 v159, v159, v75
	s_waitcnt lgkmcnt(1)
	v_mfma_f32_32x32x16_bf16 v[18:33], v[154:157], v[110:113], v[18:33]
	v_add_f32_e32 v154, v158, v92
	v_add_f32_e32 v155, v159, v76
	v_add_f32_e32 v176, v154, v93
	v_add_f32_e32 v177, v155, v77
	s_waitcnt lgkmcnt(0)
	v_mfma_f32_32x32x16_bf16 v[2:17], v[172:175], v[110:113], v[2:17]
	ds_read_b64_tr_b16 v[112:113], v171 offset:52736
	ds_read_b64_tr_b16 v[110:111], v171 offset:50176
	ds_read_b64_tr_b16 v[154:155], v171 offset:50240
	v_exp_f32_e32 v94, v94
	v_exp_f32_e32 v78, v78
	v_exp_f32_e32 v95, v95
	s_waitcnt lgkmcnt(1)
	v_mfma_f32_32x32x16_bf16 v[50:65], v[110:113], v[106:109], v[50:65]
	ds_read_b64_tr_b16 v[156:157], v171 offset:52800
	ds_read_b64_tr_b16 v[110:111], v171 offset:50304
	ds_read_b64_tr_b16 v[158:159], v171 offset:50368
	ds_read_b64_tr_b16 v[112:113], v171 offset:52864
	ds_read_b64_tr_b16 v[160:161], v171 offset:52928
	v_exp_f32_e32 v79, v79
	v_exp_f32_e32 v96, v96
	v_exp_f32_e32 v80, v80
	v_exp_f32_e32 v97, v97
	v_exp_f32_e32 v81, v81
	s_waitcnt lgkmcnt(4)
	v_mfma_f32_32x32x16_bf16 v[34:49], v[154:157], v[106:109], v[34:49]
	v_add_f32_e32 v154, v176, v94
	v_add_f32_e32 v155, v177, v78
	v_add_f32_e32 v154, v154, v95
	v_add_f32_e32 v155, v155, v79
	s_waitcnt lgkmcnt(1)
	v_mfma_f32_32x32x16_bf16 v[18:33], v[110:113], v[106:109], v[18:33]
	v_add_f32_e32 v110, v154, v96
	v_add_f32_e32 v111, v155, v80
	v_add_f32_e32 v110, v110, v97
	v_add_f32_e32 v111, v111, v81
	s_waitcnt lgkmcnt(0)
	v_mfma_f32_32x32x16_bf16 v[2:17], v[158:161], v[106:109], v[2:17]
	v_add_f32_e32 v106, v110, v111
	v_cmp_lt_f32_e32 vcc, s94, v106
	s_cbranch_vccz .LBB0_677
	v_max_f32_e32 v107, v66, v66
	v_max_f32_e32 v108, v82, v82
	v_max_f32_e32 v107, v108, v107
	v_max3_f32 v107, v107, v83, v67
	v_max3_f32 v107, v107, v84, v68
	v_max3_f32 v107, v107, v85, v69
	v_max3_f32 v107, v107, v86, v70
	v_max3_f32 v107, v107, v87, v71
	v_max3_f32 v107, v107, v88, v72
	v_max3_f32 v107, v107, v89, v73
	v_max3_f32 v107, v107, v90, v74
	v_max3_f32 v107, v107, v91, v75
	v_max3_f32 v107, v107, v92, v76
	v_max3_f32 v107, v107, v93, v77
	v_max3_f32 v107, v107, v94, v78
	v_max3_f32 v107, v107, v95, v79
	v_max3_f32 v107, v107, v96, v80
	v_max3_f32 v107, v107, v97, v81
	v_mov_b32_e32 v108, v107
	v_mov_b32_e32 v109, v107
	s_nop 1
	v_permlane32_swap_b32_e32 v108, v109
	v_cndmask_b32_e64 v108, v108, v109, s[4:5]
	v_max_f32_e32 v108, v108, v108
	v_max_f32_e32 v107, v107, v108
	v_rcp_f32_e32 v108, v107
	v_log_f32_e32 v109, v107
	v_cmp_lt_f32_e32 vcc, s95, v107
	s_nop 1
	v_cndmask_b32_e32 v108, 1.0, v108, vcc
	v_cndmask_b32_e32 v107, 0, v109, vcc
	v_mul_f32_e32 v168, v168, v108
	v_add_f32_e32 v170, v170, v107
	v_pk_mul_f32 v[64:65], v[64:65], v[108:109] op_sel_hi:[1,0]
	v_pk_mul_f32 v[62:63], v[62:63], v[108:109] op_sel_hi:[1,0]
	v_pk_mul_f32 v[60:61], v[60:61], v[108:109] op_sel_hi:[1,0]
	v_pk_mul_f32 v[58:59], v[58:59], v[108:109] op_sel_hi:[1,0]
	v_pk_mul_f32 v[56:57], v[56:57], v[108:109] op_sel_hi:[1,0]
	v_pk_mul_f32 v[54:55], v[54:55], v[108:109] op_sel_hi:[1,0]
	v_pk_mul_f32 v[52:53], v[52:53], v[108:109] op_sel_hi:[1,0]
	v_pk_mul_f32 v[50:51], v[50:51], v[108:109] op_sel_hi:[1,0]
	v_pk_mul_f32 v[48:49], v[48:49], v[108:109] op_sel_hi:[1,0]
	v_pk_mul_f32 v[46:47], v[46:47], v[108:109] op_sel_hi:[1,0]
	v_pk_mul_f32 v[44:45], v[44:45], v[108:109] op_sel_hi:[1,0]
	v_pk_mul_f32 v[42:43], v[42:43], v[108:109] op_sel_hi:[1,0]
	v_pk_mul_f32 v[40:41], v[40:41], v[108:109] op_sel_hi:[1,0]
	v_pk_mul_f32 v[38:39], v[38:39], v[108:109] op_sel_hi:[1,0]
	v_pk_mul_f32 v[36:37], v[36:37], v[108:109] op_sel_hi:[1,0]
	v_pk_mul_f32 v[34:35], v[34:35], v[108:109] op_sel_hi:[1,0]
	v_pk_mul_f32 v[32:33], v[32:33], v[108:109] op_sel_hi:[1,0]
	v_pk_mul_f32 v[30:31], v[30:31], v[108:109] op_sel_hi:[1,0]
	v_pk_mul_f32 v[28:29], v[28:29], v[108:109] op_sel_hi:[1,0]
	v_pk_mul_f32 v[26:27], v[26:27], v[108:109] op_sel_hi:[1,0]
	v_pk_mul_f32 v[24:25], v[24:25], v[108:109] op_sel_hi:[1,0]
	v_pk_mul_f32 v[22:23], v[22:23], v[108:109] op_sel_hi:[1,0]
	v_pk_mul_f32 v[20:21], v[20:21], v[108:109] op_sel_hi:[1,0]
	v_pk_mul_f32 v[18:19], v[18:19], v[108:109] op_sel_hi:[1,0]
	v_pk_mul_f32 v[16:17], v[16:17], v[108:109] op_sel_hi:[1,0]
	v_pk_mul_f32 v[14:15], v[14:15], v[108:109] op_sel_hi:[1,0]
	v_pk_mul_f32 v[12:13], v[12:13], v[108:109] op_sel_hi:[1,0]
	v_pk_mul_f32 v[10:11], v[10:11], v[108:109] op_sel_hi:[1,0]
	v_pk_mul_f32 v[8:9], v[8:9], v[108:109] op_sel_hi:[1,0]
	v_pk_mul_f32 v[6:7], v[6:7], v[108:109] op_sel_hi:[1,0]
	v_pk_mul_f32 v[4:5], v[4:5], v[108:109] op_sel_hi:[1,0]
	v_pk_mul_f32 v[2:3], v[2:3], v[108:109] op_sel_hi:[1,0]
	v_pk_mul_f32 v[96:97], v[96:97], v[108:109] op_sel_hi:[1,0]
	v_pk_mul_f32 v[94:95], v[94:95], v[108:109] op_sel_hi:[1,0]
	v_pk_mul_f32 v[92:93], v[92:93], v[108:109] op_sel_hi:[1,0]
	v_pk_mul_f32 v[90:91], v[90:91], v[108:109] op_sel_hi:[1,0]
	v_pk_mul_f32 v[88:89], v[88:89], v[108:109] op_sel_hi:[1,0]
	v_pk_mul_f32 v[86:87], v[86:87], v[108:109] op_sel_hi:[1,0]
	v_pk_mul_f32 v[84:85], v[84:85], v[108:109] op_sel_hi:[1,0]
	v_pk_mul_f32 v[82:83], v[82:83], v[108:109] op_sel_hi:[1,0]
	v_pk_mul_f32 v[80:81], v[80:81], v[108:109] op_sel_hi:[1,0]
	v_pk_mul_f32 v[78:79], v[78:79], v[108:109] op_sel_hi:[1,0]
	v_pk_mul_f32 v[76:77], v[76:77], v[108:109] op_sel_hi:[1,0]
	v_pk_mul_f32 v[74:75], v[74:75], v[108:109] op_sel_hi:[1,0]
	v_pk_mul_f32 v[72:73], v[72:73], v[108:109] op_sel_hi:[1,0]
	v_pk_mul_f32 v[70:71], v[70:71], v[108:109] op_sel_hi:[1,0]
	v_pk_mul_f32 v[68:69], v[68:69], v[108:109] op_sel_hi:[1,0]
	v_pk_mul_f32 v[66:67], v[66:67], v[108:109] op_sel_hi:[1,0]
	v_mul_f32_e32 v106, v106, v108

.LBB0_698:
	s_xor_b32 s83, s1, 1
	s_mul_i32 s84, s83, 0x5000
	v_add_u32_e32 v212, s84, v195
	ds_read_b64_tr_b16 v[202:203], v212 offset:37376
	ds_read_b64_tr_b16 v[200:201], v212 offset:34816
	ds_read_b64_tr_b16 v[204:205], v212 offset:34880
	ds_read_b64_tr_b16 v[206:207], v212 offset:37440
	s_nop 0
	v_exp_f32_e32 v82, v82
	s_nop 0
	v_exp_f32_e32 v98, v98
	s_waitcnt lgkmcnt(2)
	v_mfma_f32_32x32x16_bf16 v[50:65], v[200:203], v[174:177], v[50:65]
	ds_read_b64_tr_b16 v[200:201], v212 offset:34944
	ds_read_b64_tr_b16 v[208:209], v212 offset:35008
	ds_read_b64_tr_b16 v[202:203], v212 offset:37504
	ds_read_b64_tr_b16 v[210:211], v212 offset:37568
	v_add_f32_e32 v186, v179, v82
	v_add_f32_e32 v187, v179, v98
	v_exp_f32_e32 v83, v83
	v_exp_f32_e32 v99, v99
	s_waitcnt lgkmcnt(4)
	v_mfma_f32_32x32x16_bf16 v[34:49], v[204:207], v[174:177], v[34:49]
	v_add_f32_e32 v204, v186, v83
	v_add_f32_e32 v205, v187, v99
	v_exp_f32_e32 v186, v84
	v_exp_f32_e32 v84, v100
	v_exp_f32_e32 v187, v85
	v_exp_f32_e32 v85, v101
	v_add_f32_e32 v100, v204, v186
	s_waitcnt lgkmcnt(1)
	v_mfma_f32_32x32x16_bf16 v[18:33], v[200:203], v[174:177], v[18:33]
	v_add_f32_e32 v101, v205, v84
	v_add_f32_e32 v213, v100, v187
	v_add_f32_e32 v214, v101, v85
	s_waitcnt lgkmcnt(0)
	v_mfma_f32_32x32x16_bf16 v[2:17], v[208:211], v[174:177], v[2:17]
	ds_read_b64_tr_b16 v[176:177], v212 offset:42496
	ds_read_b64_tr_b16 v[174:175], v212 offset:39936
	ds_read_b64_tr_b16 v[200:201], v212 offset:40000
	v_exp_f32_e32 v100, v86
	v_exp_f32_e32 v86, v102
	v_exp_f32_e32 v101, v87
	s_waitcnt lgkmcnt(1)
	v_mfma_f32_32x32x16_bf16 v[50:65], v[174:177], v[162:165], v[50:65]
	ds_read_b64_tr_b16 v[202:203], v212 offset:42560
	ds_read_b64_tr_b16 v[174:175], v212 offset:40064
	ds_read_b64_tr_b16 v[204:205], v212 offset:40128
	ds_read_b64_tr_b16 v[176:177], v212 offset:42624
	ds_read_b64_tr_b16 v[206:207], v212 offset:42688
	v_exp_f32_e32 v87, v103
	v_add_f32_e32 v102, v213, v100
	v_add_f32_e32 v103, v214, v86
	s_waitcnt lgkmcnt(4)
	v_mfma_f32_32x32x16_bf16 v[34:49], v[200:203], v[162:165], v[34:49]
	v_add_f32_e32 v200, v102, v101
	v_add_f32_e32 v201, v103, v87
	v_exp_f32_e32 v102, v88
	v_exp_f32_e32 v88, v104
	v_exp_f32_e32 v103, v89
	v_exp_f32_e32 v89, v105
	v_add_f32_e32 v104, v200, v102
	s_waitcnt lgkmcnt(1)
	v_mfma_f32_32x32x16_bf16 v[18:33], v[174:177], v[162:165], v[18:33]
	v_add_f32_e32 v105, v201, v88
	v_add_f32_e32 v208, v104, v103
	v_add_f32_e32 v209, v105, v89
	s_waitcnt lgkmcnt(0)
	v_mfma_f32_32x32x16_bf16 v[2:17], v[204:207], v[162:165], v[2:17]
	ds_read_b64_tr_b16 v[164:165], v212 offset:47616
	ds_read_b64_tr_b16 v[162:163], v212 offset:45056
	ds_read_b64_tr_b16 v[174:175], v212 offset:45120
	v_exp_f32_e32 v104, v90
	v_exp_f32_e32 v90, v106
	v_exp_f32_e32 v105, v91
	s_waitcnt lgkmcnt(1)
	v_mfma_f32_32x32x16_bf16 v[50:65], v[162:165], v[158:161], v[50:65]
	ds_read_b64_tr_b16 v[176:177], v212 offset:47680
	ds_read_b64_tr_b16 v[162:163], v212 offset:45184
	ds_read_b64_tr_b16 v[200:201], v212 offset:45248
	ds_read_b64_tr_b16 v[164:165], v212 offset:47744
	ds_read_b64_tr_b16 v[202:203], v212 offset:47808
	v_exp_f32_e32 v91, v107
	v_add_f32_e32 v106, v208, v104
	v_add_f32_e32 v107, v209, v90
	s_waitcnt lgkmcnt(4)
	v_mfma_f32_32x32x16_bf16 v[34:49], v[174:177], v[158:161], v[34:49]
	v_add_f32_e32 v174, v106, v105
	v_add_f32_e32 v175, v107, v91
	v_exp_f32_e32 v106, v92
	v_exp_f32_e32 v92, v108
	v_exp_f32_e32 v107, v93
	v_exp_f32_e32 v93, v109
	v_add_f32_e32 v108, v174, v106
	s_waitcnt lgkmcnt(1)
	v_mfma_f32_32x32x16_bf16 v[18:33], v[162:165], v[158:161], v[18:33]
	v_add_f32_e32 v109, v175, v92
	v_add_f32_e32 v204, v108, v107
	v_add_f32_e32 v205, v109, v93
	s_waitcnt lgkmcnt(0)
	v_mfma_f32_32x32x16_bf16 v[2:17], v[200:203], v[158:161], v[2:17]
	ds_read_b64_tr_b16 v[160:161], v212 offset:52736
	ds_read_b64_tr_b16 v[158:159], v212 offset:50176
	ds_read_b64_tr_b16 v[162:163], v212 offset:50240
	v_exp_f32_e32 v108, v94
	v_exp_f32_e32 v94, v110
	v_exp_f32_e32 v109, v95
	s_waitcnt lgkmcnt(1)
	v_mfma_f32_32x32x16_bf16 v[50:65], v[158:161], v[154:157], v[50:65]
	ds_read_b64_tr_b16 v[164:165], v212 offset:52800
	ds_read_b64_tr_b16 v[158:159], v212 offset:50304
	ds_read_b64_tr_b16 v[174:175], v212 offset:50368
	ds_read_b64_tr_b16 v[160:161], v212 offset:52864
	ds_read_b64_tr_b16 v[176:177], v212 offset:52928
	v_exp_f32_e32 v95, v111
	v_add_f32_e32 v110, v204, v108
	v_add_f32_e32 v111, v205, v94
	s_waitcnt lgkmcnt(4)
	v_mfma_f32_32x32x16_bf16 v[34:49], v[162:165], v[154:157], v[34:49]
	v_add_f32_e32 v162, v110, v109
	v_add_f32_e32 v163, v111, v95
	v_exp_f32_e32 v110, v96
	v_exp_f32_e32 v96, v112
	v_exp_f32_e32 v111, v97
	v_exp_f32_e32 v97, v113
	v_add_f32_e32 v112, v162, v110
	s_waitcnt lgkmcnt(1)
	v_mfma_f32_32x32x16_bf16 v[18:33], v[158:161], v[154:157], v[18:33]
	v_add_f32_e32 v113, v163, v96
	v_add_f32_e32 v112, v112, v111
	v_add_f32_e32 v113, v113, v97
	s_waitcnt lgkmcnt(0)
	v_mfma_f32_32x32x16_bf16 v[2:17], v[174:177], v[154:157], v[2:17]
	v_add_f32_e32 v112, v112, v113
	v_cmp_lt_f32_e32 vcc, s94, v112
	s_cbranch_vccz .LBB0_700
	v_max_f32_e32 v66, v98, v98
	v_max_f32_e32 v67, v82, v82
	v_max_f32_e32 v66, v67, v66
	v_max3_f32 v66, v66, v83, v99
	v_max3_f32 v66, v66, v186, v84
	v_max3_f32 v66, v66, v187, v85
	v_max3_f32 v66, v66, v100, v86
	v_max3_f32 v66, v66, v101, v87
	v_max3_f32 v66, v66, v102, v88
	v_max3_f32 v66, v66, v103, v89
	v_max3_f32 v66, v66, v104, v90
	v_max3_f32 v66, v66, v105, v91
	v_max3_f32 v66, v66, v106, v92
	v_max3_f32 v66, v66, v107, v93
	v_max3_f32 v66, v66, v108, v94
	v_max3_f32 v66, v66, v109, v95
	v_max3_f32 v66, v66, v110, v96
	v_max3_f32 v66, v66, v111, v97
	v_mov_b32_e32 v67, v66
	v_mov_b32_e32 v68, v66
	s_nop 1
	v_permlane32_swap_b32_e32 v67, v68
	v_cndmask_b32_e64 v67, v67, v68, s[4:5]
	v_max_f32_e32 v67, v67, v67
	v_max_f32_e32 v66, v66, v67
	v_log_f32_e32 v69, v66
	v_rcp_f32_e32 v67, v66
	v_cmp_lt_f32_e32 vcc, s95, v66
	s_nop 1
	v_cndmask_b32_e32 v66, 0, v69, vcc
	v_add_f32_e32 v199, v199, v66
	v_cndmask_b32_e32 v68, 1.0, v67, vcc
	v_xor_b32_e32 v66, 0x80000000, v199
	v_mul_f32_e32 v198, v198, v68
	v_pk_mul_f32 v[64:65], v[64:65], v[68:69] op_sel_hi:[1,0]
	v_pk_mul_f32 v[62:63], v[62:63], v[68:69] op_sel_hi:[1,0]
	v_pk_mul_f32 v[60:61], v[60:61], v[68:69] op_sel_hi:[1,0]
	v_pk_mul_f32 v[58:59], v[58:59], v[68:69] op_sel_hi:[1,0]
	v_pk_mul_f32 v[56:57], v[56:57], v[68:69] op_sel_hi:[1,0]
	v_pk_mul_f32 v[54:55], v[54:55], v[68:69] op_sel_hi:[1,0]
	v_pk_mul_f32 v[52:53], v[52:53], v[68:69] op_sel_hi:[1,0]
	v_pk_mul_f32 v[50:51], v[50:51], v[68:69] op_sel_hi:[1,0]
	v_pk_mul_f32 v[48:49], v[48:49], v[68:69] op_sel_hi:[1,0]
	v_pk_mul_f32 v[46:47], v[46:47], v[68:69] op_sel_hi:[1,0]
	v_pk_mul_f32 v[44:45], v[44:45], v[68:69] op_sel_hi:[1,0]
	v_pk_mul_f32 v[42:43], v[42:43], v[68:69] op_sel_hi:[1,0]
	v_pk_mul_f32 v[40:41], v[40:41], v[68:69] op_sel_hi:[1,0]
	v_pk_mul_f32 v[38:39], v[38:39], v[68:69] op_sel_hi:[1,0]
	v_pk_mul_f32 v[36:37], v[36:37], v[68:69] op_sel_hi:[1,0]
	v_pk_mul_f32 v[34:35], v[34:35], v[68:69] op_sel_hi:[1,0]
	v_pk_mul_f32 v[32:33], v[32:33], v[68:69] op_sel_hi:[1,0]
	v_pk_mul_f32 v[30:31], v[30:31], v[68:69] op_sel_hi:[1,0]
	v_pk_mul_f32 v[28:29], v[28:29], v[68:69] op_sel_hi:[1,0]
	v_pk_mul_f32 v[26:27], v[26:27], v[68:69] op_sel_hi:[1,0]
	v_pk_mul_f32 v[24:25], v[24:25], v[68:69] op_sel_hi:[1,0]
	v_pk_mul_f32 v[22:23], v[22:23], v[68:69] op_sel_hi:[1,0]
	v_pk_mul_f32 v[20:21], v[20:21], v[68:69] op_sel_hi:[1,0]
	v_pk_mul_f32 v[18:19], v[18:19], v[68:69] op_sel_hi:[1,0]
	v_pk_mul_f32 v[16:17], v[16:17], v[68:69] op_sel_hi:[1,0]
	v_pk_mul_f32 v[14:15], v[14:15], v[68:69] op_sel_hi:[1,0]
	v_pk_mul_f32 v[12:13], v[12:13], v[68:69] op_sel_hi:[1,0]
	v_pk_mul_f32 v[10:11], v[10:11], v[68:69] op_sel_hi:[1,0]
	v_pk_mul_f32 v[8:9], v[8:9], v[68:69] op_sel_hi:[1,0]
	v_pk_mul_f32 v[6:7], v[6:7], v[68:69] op_sel_hi:[1,0]
	v_pk_mul_f32 v[4:5], v[4:5], v[68:69] op_sel_hi:[1,0]
	v_pk_mul_f32 v[2:3], v[2:3], v[68:69] op_sel_hi:[1,0]
	v_pk_mul_f32 v[96:97], v[96:97], v[68:69] op_sel_hi:[1,0]
	v_pk_mul_f32 v[94:95], v[94:95], v[68:69] op_sel_hi:[1,0]
	v_pk_mul_f32 v[92:93], v[92:93], v[68:69] op_sel_hi:[1,0]
	v_pk_mul_f32 v[90:91], v[90:91], v[68:69] op_sel_hi:[1,0]
	v_pk_mul_f32 v[88:89], v[88:89], v[68:69] op_sel_hi:[1,0]
	v_pk_mul_f32 v[86:87], v[86:87], v[68:69] op_sel_hi:[1,0]
	v_pk_mul_f32 v[84:85], v[84:85], v[68:69] op_sel_hi:[1,0]
	v_pk_mul_f32 v[98:99], v[98:99], v[68:69] op_sel_hi:[1,0]
	v_pk_mul_f32 v[110:111], v[110:111], v[68:69] op_sel_hi:[1,0]
	v_pk_mul_f32 v[108:109], v[108:109], v[68:69] op_sel_hi:[1,0]
	v_pk_mul_f32 v[106:107], v[106:107], v[68:69] op_sel_hi:[1,0]
	v_pk_mul_f32 v[104:105], v[104:105], v[68:69] op_sel_hi:[1,0]
	v_pk_mul_f32 v[102:103], v[102:103], v[68:69] op_sel_hi:[1,0]
	v_pk_mul_f32 v[100:101], v[100:101], v[68:69] op_sel_hi:[1,0]
	v_pk_mul_f32 v[186:187], v[186:187], v[68:69] op_sel_hi:[1,0]
	v_pk_mul_f32 v[82:83], v[82:83], v[68:69] op_sel_hi:[1,0]
	v_mul_f32_e32 v112, v112, v68
	v_mov_b32_e32 v67, v66
	v_mov_b32_e32 v68, v66
	v_mov_b32_e32 v69, v66
	v_mov_b32_e32 v70, v66
	v_mov_b32_e32 v71, v66
	v_mov_b32_e32 v72, v66
	v_mov_b32_e32 v73, v66
	v_mov_b32_e32 v74, v66
	v_mov_b32_e32 v75, v66
	v_mov_b32_e32 v76, v66
	v_mov_b32_e32 v77, v66
	v_mov_b32_e32 v78, v66
	v_mov_b32_e32 v79, v66
	v_mov_b32_e32 v80, v66
	v_mov_b32_e32 v81, v66
